# attention->W_out boundary XCC-local too; the one cross-batch hazard left (gate/up output rows of batch b re-use the tail of batch b-1's attention input) is ordered by a per-batch done flag the XCC lea
# speedup vs baseline: 1.0273x; 1.0101x over previous
; __device__ __forceinline__ unsigned xb_add(unsigned* p, unsigned v) { return __hip_atomic_fetch_add(p, v, __ATOMIC_RELAXED, __HIP_MEMORY_SCOPE_AGENT); }
; __device__ __forceinline__ void xcd_barrier(const XcdBarrier& b, const int tid) {
;     asm volatile("s_waitcnt vmcnt(0)" ::: "memory");
;     __syncthreads();
;     if (tid == 0) {
;         unsigned* bar = b.bar;
;         __builtin_amdgcn_s_waitcnt(0);
;         unsigned nloc = b.st[0], nx = b.st[1];
;         if (nloc == 0u) { xcd_barrier_complete(bar, b.x, nloc, nx); b.st[0] = nloc; b.st[1] = nx; }
;         const unsigned old = xb_add(&bar[XB_XSUB(b.x)], 1u);
;         const unsigned gen = old / nloc;
;         if (old + 1u == (gen + 1u) * nloc) {
.Lxb_nf2:
	s_cmp_eq_u32 s48, 3
	s_cbranch_scc0 .Lxb_nf3
	v_readlane_b32 s4, v252, 12
	v_readlane_b32 s5, v252, 13
	s_nop 4
	global_load_dword v4, v1, s[4:5] offset:2052 sc1
	v_readlane_b32 s5, v251, 11
	s_waitcnt vmcnt(0)
	v_readfirstlane_b32 s4, v4
	s_cmp_eq_u32 s4, 0
	s_cselect_b32 s4, 1, 0
	s_cmp_eq_u32 s5, 0x4000
	s_cselect_b32 s4, s4, 0
	v_readlane_b32 s5, v251, 34
	s_nop 1
	v_mov_b32_e32 v5, s5
	ds_read_b32 v5, v5
	s_waitcnt lgkmcnt(0)
	v_readfirstlane_b32 s5, v5
	s_cmp_eq_u32 s5, 32
	s_cselect_b32 s4, s4, 0
	s_nop 1
	v_writelane_b32 v255, s4, 21
	s_nop 1
.Lxb_nf3:
	s_movk_i32 s4, 0xf78
	s_lshr_b32 s4, s4, s48
	v_readlane_b32 s5, v255, 21
	s_and_b32 s4, s4, 1
	s_and_b32 s99, s4, s5

; __device__ __forceinline__ unsigned xb_ld(unsigned* p)              { return __hip_atomic_load(p, __ATOMIC_RELAXED, __HIP_MEMORY_SCOPE_AGENT); }
; __device__ __forceinline__ unsigned xb_add(unsigned* p, unsigned v) { return __hip_atomic_fetch_add(p, v, __ATOMIC_RELAXED, __HIP_MEMORY_SCOPE_AGENT); }
; #define XB_SPIN(cond, bar) do { unsigned _sp = 0; while (cond) { __builtin_amdgcn_s_sleep(1); \
;     if ((++_sp & 255u) == 0u) { if (xb_ld(&(bar)[XB_TMO])) break; if (_sp > XB_SPIN_CAP) { atomicAdd(&(bar)[XB_TMO], 1u); break; } } } } while (0)
; __device__ __forceinline__ void xcd_barrier(const XcdBarrier& b, const int tid) {
;     ...
;         const unsigned old = xb_add(&bar[XB_XSUB(b.x)], 1u);
;         const unsigned gen = old / nloc;
;         if (old + 1u == (gen + 1u) * nloc) {
;             __builtin_amdgcn_fence(__ATOMIC_RELEASE, "agent");
;             asm volatile("s_waitcnt vmcnt(0)" ::: "memory");
;             const unsigned og = xb_add(&bar[XB_TOP], 1u);
;             const unsigned tg = og / nx;
;             if (og + 1u == (tg + 1u) * nx) xb_add(&bar[XB_TOPGEN], 1u);
;             else XB_SPIN(xb_ld(&bar[XB_TOPGEN]) == tg, bar);
;             __builtin_amdgcn_fence(__ATOMIC_ACQUIRE, "agent");
;             xb_add(&bar[XB_XGEN(b.x)], 1u);
;             asm volatile("s_waitcnt vmcnt(0)" ::: "memory");
;         } else {
;             XB_SPIN(xb_ld(&bar[XB_XGEN(b.x)]) == gen, bar);
;             __builtin_amdgcn_fence(__ATOMIC_ACQUIRE, "agent");
;             asm volatile("s_waitcnt vmcnt(0)" ::: "memory");
;         }
.LBB0_602:
	s_andn2_saveexec_b64 s[2:3], s[2:3]
	s_cbranch_execz .LBB0_622
	s_mov_b64 s[2:3], exec
	s_cmp_eq_u32 s99, 1
	s_cbranch_scc0 .Lxb_glob
	s_cmp_eq_u32 s48, 4
	s_cbranch_scc1 .Lxb_pub
	s_cmp_eq_u32 s48, 9
	s_cbranch_scc1 .Lxb_pub
	s_cmp_eq_u32 s48, 5
	s_cbranch_scc1 .Lxb_wt
	s_cmp_eq_u32 s48, 10
	s_cbranch_scc1 .Lxb_wt
	s_branch .Lxb_rel
.Lxb_pub:
	v_readlane_b32 s5, v249, 0
	s_and_b32 s5, s5, 7
	s_lshl_b32 s5, s5, 2
	v_mov_b32_e32 v5, s5
	v_mov_b32_e32 v4, s48
	v_readlane_b32 s4, v252, 12
	v_readlane_b32 s5, v252, 13
	s_nop 4
	global_store_dword v5, v4, s[4:5] offset:2112 sc1
	s_waitcnt vmcnt(0)
	s_branch .Lxb_rel
.Lxb_wt:
	v_readlane_b32 s5, v249, 0
	s_and_b32 s5, s5, 7
	s_cmp_eq_u32 s5, 0
	s_cbranch_scc1 .Lxb_rel
	s_add_i32 s5, s5, -1
	s_lshl_b32 s5, s5, 2
	v_mov_b32_e32 v5, s5
	s_add_i32 s6, s48, -1
	s_mov_b32 s7, 0
	v_readlane_b32 s4, v252, 12
	v_readlane_b32 s5, v252, 13
	s_nop 4
.Lxb_wt_loop:
	global_load_dword v4, v5, s[4:5] offset:2112 sc1
	s_waitcnt vmcnt(0)
	v_readfirstlane_b32 s8, v4
	s_cmp_ge_u32 s8, s6
	s_cbranch_scc1 .Lxb_rel
	s_sleep 1
	s_add_i32 s7, s7, 1
	s_cmp_lt_u32 s7, 0x4000
	s_cbranch_scc1 .Lxb_wt_loop
.Lxb_rel:
	v_readlane_b32 s4, v250, 11
	v_readlane_b32 s5, v250, 12
	v_mov_b32_e32 v4, 1
	s_nop 4
	global_atomic_add v1, v4, s[4:5]
	s_mov_b64 s[4:5], 0
	s_branch .LBB0_617
